# prep short-conv: all 15 Z row loads per token hoisted (1 round trip instead of 15); delta-scan loop tail no longer waits for its result stores
# speedup vs baseline: 1.0188x; 1.0188x over previous
.LBB0_227:
	v_and_b32_sdwa v2, v61, v1 dst_sel:DWORD dst_unused:UNUSED_PAD src0_sel:WORD_1 src1_sel:DWORD
	v_and_b32_sdwa v3, v60, v1 dst_sel:DWORD dst_unused:UNUSED_PAD src0_sel:WORD_1 src1_sel:DWORD
	v_add3_u32 v2, v61, v2, s26
	v_add3_u32 v78, v60, v3, s26
	v_and_b32_e32 v3, 0xffff0000, v2
	v_and_b32_e32 v2, 0xffff0000, v78
	v_pk_add_f32 v[6:7], v[60:61], v[2:3] neg_lo:[0,1] neg_hi:[0,1]
	v_and_b32_sdwa v2, v63, v1 dst_sel:DWORD dst_unused:UNUSED_PAD src0_sel:WORD_1 src1_sel:DWORD
	v_and_b32_sdwa v4, v62, v1 dst_sel:DWORD dst_unused:UNUSED_PAD src0_sel:WORD_1 src1_sel:DWORD
	v_add3_u32 v2, v63, v2, s26
	v_add3_u32 v79, v62, v4, s26
	v_and_b32_e32 v5, 0xffff0000, v2
	v_and_b32_e32 v4, 0xffff0000, v79
	v_pk_add_f32 v[8:9], v[62:63], v[4:5] neg_lo:[0,1] neg_hi:[0,1]
	v_and_b32_sdwa v2, v59, v1 dst_sel:DWORD dst_unused:UNUSED_PAD src0_sel:WORD_1 src1_sel:DWORD
	v_and_b32_sdwa v4, v58, v1 dst_sel:DWORD dst_unused:UNUSED_PAD src0_sel:WORD_1 src1_sel:DWORD
	v_add3_u32 v2, v59, v2, s26
	v_add3_u32 v4, v58, v4, s26
	v_and_b32_e32 v11, 0xffff0000, v2
	v_and_b32_e32 v10, 0xffff0000, v4
	v_and_b32_sdwa v2, v65, v1 dst_sel:DWORD dst_unused:UNUSED_PAD src0_sel:WORD_1 src1_sel:DWORD
	v_pk_add_f32 v[12:13], v[58:59], v[10:11] neg_lo:[0,1] neg_hi:[0,1]
	v_and_b32_sdwa v10, v64, v1 dst_sel:DWORD dst_unused:UNUSED_PAD src0_sel:WORD_1 src1_sel:DWORD
	v_add3_u32 v2, v65, v2, s26
	v_add3_u32 v10, v64, v10, s26
	v_and_b32_e32 v15, 0xffff0000, v2
	v_and_b32_e32 v14, 0xffff0000, v10
	v_or_b32_sdwa v2, v3, v78 dst_sel:DWORD dst_unused:UNUSED_PAD src0_sel:DWORD src1_sel:WORD_1
	v_or_b32_sdwa v3, v11, v4 dst_sel:DWORD dst_unused:UNUSED_PAD src0_sel:DWORD src1_sel:WORD_1
	v_or_b32_sdwa v4, v5, v79 dst_sel:DWORD dst_unused:UNUSED_PAD src0_sel:DWORD src1_sel:WORD_1
	v_or_b32_sdwa v5, v15, v10 dst_sel:DWORD dst_unused:UNUSED_PAD src0_sel:DWORD src1_sel:WORD_1
	v_and_b32_sdwa v10, v67, v1 dst_sel:DWORD dst_unused:UNUSED_PAD src0_sel:WORD_1 src1_sel:DWORD
	v_and_b32_sdwa v11, v66, v1 dst_sel:DWORD dst_unused:UNUSED_PAD src0_sel:WORD_1 src1_sel:DWORD
	v_pk_add_f32 v[16:17], v[64:65], v[14:15] neg_lo:[0,1] neg_hi:[0,1]
	v_add3_u32 v10, v67, v10, s26
	v_add3_u32 v14, v66, v11, s26
	v_and_b32_e32 v11, 0xffff0000, v10
	v_and_b32_e32 v10, 0xffff0000, v14
	v_pk_add_f32 v[78:79], v[66:67], v[10:11] neg_lo:[0,1] neg_hi:[0,1]
	v_and_b32_sdwa v10, v71, v1 dst_sel:DWORD dst_unused:UNUSED_PAD src0_sel:WORD_1 src1_sel:DWORD
	v_add3_u32 v10, v71, v10, s26
	v_cvt_pk_bf16_f32 v6, v6, v7
	v_cvt_pk_bf16_f32 v7, v12, v13
	v_and_b32_e32 v13, 0xffff0000, v10
	v_and_b32_sdwa v10, v69, v1 dst_sel:DWORD dst_unused:UNUSED_PAD src0_sel:WORD_1 src1_sel:DWORD
	s_and_b32 s6, s40, 0x8000
	v_add3_u32 v10, v69, v10, s26
	v_and_b32_e32 v101, 0xffff0000, v10
	v_and_b32_sdwa v10, v73, v1 dst_sel:DWORD dst_unused:UNUSED_PAD src0_sel:WORD_1 src1_sel:DWORD
	v_add_u32_e32 v149, s6, v112
	v_and_b32_sdwa v12, v70, v1 dst_sel:DWORD dst_unused:UNUSED_PAD src0_sel:WORD_1 src1_sel:DWORD
	v_and_b32_sdwa v15, v72, v1 dst_sel:DWORD dst_unused:UNUSED_PAD src0_sel:WORD_1 src1_sel:DWORD
	v_add3_u32 v10, v73, v10, s26
	v_add_u32_e32 v184, v149, v23
	v_add_u32_e32 v185, v149, v95
	v_cvt_pk_bf16_f32 v8, v8, v9
	v_cvt_pk_bf16_f32 v9, v16, v17
	v_add3_u32 v102, v70, v12, s26
	v_add3_u32 v146, v72, v15, s26
	v_and_b32_e32 v145, 0xffff0000, v10
	v_or_b32_sdwa v10, v11, v14 dst_sel:DWORD dst_unused:UNUSED_PAD src0_sel:DWORD src1_sel:WORD_1
	ds_read2st64_b64 v[14:17], v184 offset1:4
	ds_read2st64_b64 v[96:99], v185 offset1:4
	v_and_b32_e32 v12, 0xffff0000, v102
	v_pk_add_f32 v[108:109], v[70:71], v[12:13] neg_lo:[0,1] neg_hi:[0,1]
	v_and_b32_sdwa v12, v68, v1 dst_sel:DWORD dst_unused:UNUSED_PAD src0_sel:WORD_1 src1_sel:DWORD
	v_add3_u32 v12, v68, v12, s26
	v_and_b32_e32 v100, 0xffff0000, v12
	v_pk_add_f32 v[162:163], v[68:69], v[100:101] neg_lo:[0,1] neg_hi:[0,1]
	v_or_b32_sdwa v11, v101, v12 dst_sel:DWORD dst_unused:UNUSED_PAD src0_sel:DWORD src1_sel:WORD_1
	v_or_b32_sdwa v12, v13, v102 dst_sel:DWORD dst_unused:UNUSED_PAD src0_sel:DWORD src1_sel:WORD_1
	s_waitcnt lgkmcnt(0)
	v_mov_b32_e32 v100, v14
	v_mov_b32_e32 v101, v15
	v_mov_b32_e32 v102, v96
	v_mov_b32_e32 v103, v97
	v_mov_b32_e32 v96, v16
	v_mov_b32_e32 v97, v17
	v_and_b32_e32 v144, 0xffff0000, v146
	v_pk_add_f32 v[170:171], v[72:73], v[144:145] neg_lo:[0,1] neg_hi:[0,1]
	ds_read2st64_b64 v[104:107], v184 offset0:16 offset1:20
	v_or_b32_sdwa v13, v145, v146 dst_sel:DWORD dst_unused:UNUSED_PAD src0_sel:DWORD src1_sel:WORD_1
	ds_read2st64_b64 v[144:147], v185 offset0:16 offset1:20
	v_mfma_f32_16x16x32_bf16 v[154:157], v[100:103], v[2:5], 0
	v_add_u32_e32 v186, v149, v110
	v_add_u32_e32 v187, v149, v111
	s_waitcnt lgkmcnt(1)
	v_mov_b32_e32 v150, v104
	v_mfma_f32_16x16x32_bf16 v[14:17], v[96:99], v[2:5], 0
	v_mov_b32_e32 v151, v105
	s_waitcnt lgkmcnt(0)
	v_mov_b32_e32 v152, v144
	v_mov_b32_e32 v153, v145
	v_mfma_f32_16x16x32_bf16 v[100:103], v[100:103], v[6:9], v[154:157]
	ds_read2st64_b64 v[158:161], v187 offset1:4
	v_mov_b32_e32 v144, v106
	v_mov_b32_e32 v145, v107
	ds_read2st64_b64 v[154:157], v186 offset1:4
	v_mfma_f32_16x16x32_bf16 v[14:17], v[96:99], v[6:9], v[14:17]
	v_cvt_pk_bf16_f32 v149, v162, v163
	ds_read2st64_b64 v[162:165], v186 offset0:16 offset1:20
	ds_read2st64_b64 v[166:169], v187 offset0:16 offset1:20
	v_mfma_f32_16x16x32_bf16 v[100:103], v[150:153], v[2:5], v[100:103]
	s_waitcnt lgkmcnt(2)
	v_mov_b32_e32 v152, v154
	v_mov_b32_e32 v153, v155
	v_mov_b32_e32 v154, v158
	v_mov_b32_e32 v155, v159
	v_mov_b32_e32 v158, v156
	v_mov_b32_e32 v159, v157
	v_mfma_f32_16x16x32_bf16 v[14:17], v[144:147], v[2:5], v[14:17]
	ds_read2st64_b64 v[96:99], v184 offset0:8 offset1:12
	ds_read2st64_b64 v[104:107], v185 offset0:8 offset1:12
	v_cvt_pk_bf16_f32 v148, v78, v79
	v_mfma_f32_16x16x32_bf16 v[14:17], v[158:161], v[10:13], v[14:17]
	v_cvt_pk_bf16_f32 v150, v108, v109
	v_cvt_pk_bf16_f32 v151, v170, v171
	s_waitcnt lgkmcnt(2)
	v_mov_b32_e32 v172, v166
	v_mov_b32_e32 v173, v167
	v_mov_b32_e32 v166, v164
	v_mov_b32_e32 v167, v165
	v_mfma_f32_16x16x32_bf16 v[100:103], v[152:155], v[10:13], v[100:103]
	s_waitcnt lgkmcnt(1)
	v_mov_b32_e32 v144, v96
	v_mov_b32_e32 v145, v97
	s_waitcnt lgkmcnt(0)
	v_mov_b32_e32 v146, v104
	v_mfma_f32_16x16x32_bf16 v[14:17], v[158:161], v[148:151], v[14:17]
	v_mov_b32_e32 v147, v105
	v_mov_b32_e32 v104, v98
	v_mov_b32_e32 v105, v99
	v_mov_b32_e32 v170, v162
	v_mov_b32_e32 v171, v163
	v_mfma_f32_16x16x32_bf16 v[100:103], v[152:155], v[148:151], v[100:103]
	ds_read2st64_b64 v[152:155], v184 offset0:24 offset1:28
	s_add_i32 s44, s44, s39
	s_lshl_b32 s6, s44, 3
	v_mfma_f32_16x16x32_bf16 v[156:159], v[166:169], v[10:13], v[14:17]
	s_or_b32 s6, s6, s42
	s_waitcnt lgkmcnt(0)
	v_mov_b32_e32 v160, v152
	v_mov_b32_e32 v161, v153
	ds_read2st64_b64 v[14:17], v185 offset0:24 offset1:28
	v_mfma_f32_16x16x32_bf16 v[164:167], v[144:147], v[2:5], 0
	s_ashr_i32 s7, s6, 31
	s_add_i32 s41, s41, -1
	s_add_i32 s40, s40, 0x8000
	v_mfma_f32_16x16x32_bf16 v[96:99], v[104:107], v[2:5], 0
	s_waitcnt lgkmcnt(0)
	v_mov_b32_e32 v162, v14
	v_mov_b32_e32 v163, v15
	v_mov_b32_e32 v14, v154
	v_mfma_f32_16x16x32_bf16 v[100:103], v[170:173], v[10:13], v[100:103]
	v_mov_b32_e32 v15, v155
	s_cmp_eq_u32 s43, s38
	v_mfma_f32_16x16x32_bf16 v[144:147], v[144:147], v[6:9], v[164:167]
	s_nop 2
	ds_read2st64_b64 v[164:167], v186 offset0:8 offset1:12
	ds_read2st64_b64 v[168:171], v187 offset0:8 offset1:12
	ds_read2st64_b64 v[172:175], v186 offset0:24 offset1:28
	ds_read2st64_b64 v[176:179], v187 offset0:24 offset1:28
	v_sub_f32_e32 v78, v138, v100
	v_mfma_f32_16x16x32_bf16 v[6:9], v[104:107], v[6:9], v[96:99]
	v_sub_f32_e32 v102, v140, v102
	s_waitcnt lgkmcnt(1)
	v_mov_b32_e32 v180, v172
	v_mov_b32_e32 v181, v173
	v_mfma_f32_16x16x32_bf16 v[144:147], v[160:163], v[2:5], v[144:147]
	v_mov_b32_e32 v160, v164
	v_mov_b32_e32 v161, v165
	v_mov_b32_e32 v162, v168
	v_mov_b32_e32 v163, v169
	v_mov_b32_e32 v168, v166
	v_mov_b32_e32 v169, v167
	v_mfma_f32_16x16x32_bf16 v[2:5], v[14:17], v[2:5], v[6:9]
	s_waitcnt lgkmcnt(0)
	v_mov_b32_e32 v182, v176
	v_mov_b32_e32 v183, v177
	v_mov_b32_e32 v176, v174
	v_mfma_f32_16x16x32_bf16 v[144:147], v[160:163], v[10:13], v[144:147]
	v_mov_b32_e32 v177, v175
	v_sub_f32_e32 v79, v139, v101
	v_and_b32_sdwa v7, v78, v1 dst_sel:DWORD dst_unused:UNUSED_PAD src0_sel:WORD_1 src1_sel:DWORD
	v_mfma_f32_16x16x32_bf16 v[2:5], v[168:171], v[10:13], v[2:5]
	v_sub_f32_e32 v103, v141, v103
	v_add3_u32 v14, v78, v7, s26
	v_and_b32_sdwa v7, v102, v1 dst_sel:DWORD dst_unused:UNUSED_PAD src0_sel:WORD_1 src1_sel:DWORD
	v_mfma_f32_16x16x32_bf16 v[144:147], v[160:163], v[148:151], v[144:147]
	v_and_b32_sdwa v8, v79, v1 dst_sel:DWORD dst_unused:UNUSED_PAD src0_sel:WORD_1 src1_sel:DWORD
	v_and_b32_sdwa v6, v103, v1 dst_sel:DWORD dst_unused:UNUSED_PAD src0_sel:WORD_1 src1_sel:DWORD
	v_add3_u32 v15, v102, v7, s26
	v_mfma_f32_16x16x32_bf16 v[2:5], v[168:171], v[148:151], v[2:5]
	v_add3_u32 v7, v79, v8, s26
	v_and_b32_e32 v7, 0xffff0000, v7
	v_sub_f32_e32 v106, v18, v156
	v_mfma_f32_16x16x32_bf16 v[144:147], v[180:183], v[10:13], v[144:147]
	v_sub_f32_e32 v99, v21, v159
	v_sub_f32_e32 v98, v20, v158
	v_sub_f32_e32 v107, v19, v157
	v_mfma_f32_16x16x32_bf16 v[2:5], v[176:179], v[10:13], v[2:5]
	v_add3_u32 v11, v103, v6, s26
	v_and_b32_e32 v6, 0xffff0000, v14
	v_pk_add_f32 v[8:9], v[78:79], v[6:7] neg_lo:[0,1] neg_hi:[0,1]
	v_and_b32_e32 v10, 0xffff0000, v15
	v_and_b32_e32 v11, 0xffff0000, v11
	v_or_b32_sdwa v14, v14, v7 dst_sel:DWORD dst_unused:UNUSED_PAD src0_sel:WORD_1 src1_sel:DWORD
	v_and_b32_sdwa v7, v106, v1 dst_sel:DWORD dst_unused:UNUSED_PAD src0_sel:WORD_1 src1_sel:DWORD
	v_pk_add_f32 v[12:13], v[102:103], v[10:11] neg_lo:[0,1] neg_hi:[0,1]
	v_and_b32_sdwa v6, v99, v1 dst_sel:DWORD dst_unused:UNUSED_PAD src0_sel:WORD_1 src1_sel:DWORD
	v_add3_u32 v18, v106, v7, s26
	v_and_b32_sdwa v7, v98, v1 dst_sel:DWORD dst_unused:UNUSED_PAD src0_sel:WORD_1 src1_sel:DWORD
	v_and_b32_sdwa v10, v107, v1 dst_sel:DWORD dst_unused:UNUSED_PAD src0_sel:WORD_1 src1_sel:DWORD
	v_add3_u32 v17, v99, v6, s26
	v_add3_u32 v19, v98, v7, s26
	v_add3_u32 v7, v107, v10, s26
	v_and_b32_e32 v6, 0xffff0000, v18
	v_and_b32_e32 v7, 0xffff0000, v7
	v_and_b32_e32 v16, 0xffff0000, v19
	v_and_b32_e32 v17, 0xffff0000, v17
	v_sub_f32_e32 v108, v132, v144
	v_or_b32_sdwa v15, v11, v15 dst_sel:DWORD dst_unused:UNUSED_PAD src0_sel:DWORD src1_sel:WORD_1
	v_pk_add_f32 v[10:11], v[106:107], v[6:7] neg_lo:[0,1] neg_hi:[0,1]
	v_pk_add_f32 v[96:97], v[98:99], v[16:17] neg_lo:[0,1] neg_hi:[0,1]
	v_or_b32_sdwa v16, v18, v7 dst_sel:DWORD dst_unused:UNUSED_PAD src0_sel:WORD_1 src1_sel:DWORD
	v_sub_f32_e32 v101, v137, v147
	v_sub_f32_e32 v100, v136, v146
	v_sub_f32_e32 v109, v134, v145
	v_and_b32_sdwa v7, v108, v1 dst_sel:DWORD dst_unused:UNUSED_PAD src0_sel:WORD_1 src1_sel:DWORD
	v_cvt_pk_bf16_f32 v18, v8, v9
	v_cvt_pk_bf16_f32 v20, v10, v11
	v_cvt_pk_bf16_f32 v21, v96, v97
	v_and_b32_sdwa v6, v101, v1 dst_sel:DWORD dst_unused:UNUSED_PAD src0_sel:WORD_1 src1_sel:DWORD
	v_add3_u32 v10, v108, v7, s26
	v_and_b32_sdwa v7, v100, v1 dst_sel:DWORD dst_unused:UNUSED_PAD src0_sel:WORD_1 src1_sel:DWORD
	v_and_b32_sdwa v8, v109, v1 dst_sel:DWORD dst_unused:UNUSED_PAD src0_sel:WORD_1 src1_sel:DWORD
	v_sub_f32_e32 v97, v126, v5
	v_sub_f32_e32 v104, v120, v2
	v_add3_u32 v9, v101, v6, s26
	v_add3_u32 v11, v100, v7, s26
	v_add3_u32 v7, v109, v8, s26
	v_sub_f32_e32 v96, v125, v4
	v_sub_f32_e32 v105, v123, v3
	v_and_b32_sdwa v2, v97, v1 dst_sel:DWORD dst_unused:UNUSED_PAD src0_sel:WORD_1 src1_sel:DWORD
	v_and_b32_sdwa v3, v104, v1 dst_sel:DWORD dst_unused:UNUSED_PAD src0_sel:WORD_1 src1_sel:DWORD
	v_and_b32_e32 v6, 0xffff0000, v10
	v_and_b32_e32 v7, 0xffff0000, v7
	v_and_b32_e32 v8, 0xffff0000, v11
	v_and_b32_e32 v9, 0xffff0000, v9
	v_add3_u32 v4, v97, v2, s26
	v_add3_u32 v120, v104, v3, s26
	v_and_b32_sdwa v3, v96, v1 dst_sel:DWORD dst_unused:UNUSED_PAD src0_sel:WORD_1 src1_sel:DWORD
	v_and_b32_sdwa v5, v105, v1 dst_sel:DWORD dst_unused:UNUSED_PAD src0_sel:WORD_1 src1_sel:DWORD
	v_or_b32_sdwa v17, v17, v19 dst_sel:DWORD dst_unused:UNUSED_PAD src0_sel:DWORD src1_sel:WORD_1
	v_cvt_pk_bf16_f32 v19, v12, v13
	v_pk_add_f32 v[12:13], v[108:109], v[6:7] neg_lo:[0,1] neg_hi:[0,1]
	v_pk_add_f32 v[140:141], v[100:101], v[8:9] neg_lo:[0,1] neg_hi:[0,1]
	v_or_b32_sdwa v137, v9, v11 dst_sel:DWORD dst_unused:UNUSED_PAD src0_sel:DWORD src1_sel:WORD_1
	v_or_b32_sdwa v136, v10, v7 dst_sel:DWORD dst_unused:UNUSED_PAD src0_sel:WORD_1 src1_sel:DWORD
	v_add3_u32 v123, v96, v3, s26
	v_add3_u32 v3, v105, v5, s26
	v_and_b32_e32 v139, 0xffff0000, v4
	ds_read2st64_b64 v[4:7], v184 offset0:32 offset1:36
	ds_read2st64_b64 v[8:11], v185 offset0:32 offset1:36
	v_and_b32_e32 v2, 0xffff0000, v120
	v_and_b32_e32 v3, 0xffff0000, v3
	v_and_b32_e32 v138, 0xffff0000, v123
	v_pk_add_f32 v[162:163], v[104:105], v[2:3] neg_lo:[0,1] neg_hi:[0,1]
	v_pk_add_f32 v[176:177], v[96:97], v[138:139] neg_lo:[0,1] neg_hi:[0,1]
	v_or_b32_sdwa v138, v120, v3 dst_sel:DWORD dst_unused:UNUSED_PAD src0_sel:WORD_1 src1_sel:DWORD
	s_waitcnt lgkmcnt(1)
	v_mov_b32_e32 v2, v4
	v_mov_b32_e32 v3, v5
	s_waitcnt lgkmcnt(0)
	v_mov_b32_e32 v4, v8
	v_mov_b32_e32 v5, v9
	ds_read2st64_b64 v[144:147], v184 offset0:48 offset1:52
	v_pk_mul_f32 v[148:149], v[94:95], v[60:61] op_sel_hi:[0,1]
	ds_read2st64_b64 v[152:155], v185 offset0:48 offset1:52
	v_pk_mul_f32 v[150:151], v[94:95], v[58:59] op_sel_hi:[0,1]
	ds_read2st64_b64 v[164:167], v187 offset0:32 offset1:36
	s_waitcnt lgkmcnt(2)
	v_mov_b32_e32 v156, v144
	v_mfma_f32_16x16x32_bf16 v[148:151], v[2:5], v[14:17], v[148:151]
	v_mov_b32_e32 v157, v145
	s_waitcnt lgkmcnt(1)
	v_mov_b32_e32 v158, v152
	v_mov_b32_e32 v159, v153
	v_mfma_f32_16x16x32_bf16 v[2:5], v[2:5], v[18:21], v[148:151]
	v_or_b32_sdwa v139, v139, v123 dst_sel:DWORD dst_unused:UNUSED_PAD src0_sel:DWORD src1_sel:WORD_1
	v_mov_b32_e32 v8, v6
	v_mov_b32_e32 v9, v7
	ds_read2st64_b64 v[148:151], v186 offset0:32 offset1:36
	v_mfma_f32_16x16x32_bf16 v[2:5], v[156:159], v[14:17], v[2:5]
	s_waitcnt lgkmcnt(1)
	v_mov_b32_e32 v158, v164
	v_mov_b32_e32 v159, v165
	v_cvt_pk_bf16_f32 v160, v12, v13
	s_waitcnt lgkmcnt(0)
	v_mov_b32_e32 v156, v148
	v_mov_b32_e32 v157, v149
	v_cvt_pk_bf16_f32 v161, v140, v141
	v_cvt_pk_bf16_f32 v162, v162, v163
	v_mfma_f32_16x16x32_bf16 v[2:5], v[156:159], v[136:139], v[2:5]
	v_cvt_pk_bf16_f32 v163, v176, v177
	v_mov_b32_e32 v152, v146
	v_mov_b32_e32 v153, v147
	v_mfma_f32_16x16x32_bf16 v[2:5], v[156:159], v[160:163], v[2:5]
	v_mul_f32_e64 v156, v94, v62
	v_mul_f32_e64 v157, v94, v63
	v_pk_mul_f32 v[158:159], v[94:95], v[64:65] op_sel_hi:[0,1]
	ds_read2st64_b64 v[168:171], v186 offset0:48 offset1:52
	ds_read2st64_b64 v[172:175], v187 offset0:48 offset1:52
	v_mfma_f32_16x16x32_bf16 v[156:159], v[8:11], v[14:17], v[156:159]
	v_mov_b32_e32 v164, v150
	v_mov_b32_e32 v165, v151
	ds_read2st64_b64 v[144:147], v184 offset0:40 offset1:44
	ds_read2st64_b64 v[148:151], v185 offset0:40 offset1:44
	v_mfma_f32_16x16x32_bf16 v[6:9], v[8:11], v[18:21], v[156:159]
	s_waitcnt lgkmcnt(2)
	v_mov_b32_e32 v178, v172
	v_mov_b32_e32 v179, v173
	s_waitcnt lgkmcnt(1)
	v_mov_b32_e32 v10, v144
	v_mfma_f32_16x16x32_bf16 v[6:9], v[152:155], v[14:17], v[6:9]
	v_mov_b32_e32 v11, v145
	s_waitcnt lgkmcnt(0)
	v_mov_b32_e32 v12, v148
	v_mov_b32_e32 v13, v149
	v_mfma_f32_16x16x32_bf16 v[6:9], v[164:167], v[136:139], v[6:9]
	v_mov_b32_e32 v148, v146
	v_mov_b32_e32 v149, v147
	v_mov_b32_e32 v172, v170
	v_mov_b32_e32 v173, v171
	v_mfma_f32_16x16x32_bf16 v[6:9], v[164:167], v[160:163], v[6:9]
	ds_read2st64_b64 v[152:155], v184 offset0:56 offset1:60
	v_pk_mul_f32 v[156:157], v[94:95], v[66:67] op_sel_hi:[0,1]
	ds_read2st64_b64 v[164:167], v185 offset0:56 offset1:60
	v_pk_mul_f32 v[158:159], v[94:95], v[68:69] op_sel_hi:[0,1]
	v_pk_mul_f32 v[144:145], v[94:95], v[70:71] op_sel_hi:[0,1]
	v_pk_mul_f32 v[146:147], v[94:95], v[72:73] op_sel_hi:[0,1]
	v_mfma_f32_16x16x32_bf16 v[156:159], v[10:13], v[14:17], v[156:159]
	v_mov_b32_e32 v176, v168
	v_mov_b32_e32 v177, v169
	s_waitcnt lgkmcnt(1)
	v_mov_b32_e32 v168, v152
	v_mfma_f32_16x16x32_bf16 v[144:147], v[148:151], v[14:17], v[144:147]
	v_mov_b32_e32 v169, v153
	s_waitcnt lgkmcnt(0)
	v_mov_b32_e32 v170, v164
	v_mov_b32_e32 v171, v165
	v_mfma_f32_16x16x32_bf16 v[6:9], v[172:175], v[136:139], v[6:9]
	v_mov_b32_e32 v164, v154
	v_mov_b32_e32 v165, v155
	v_mfma_f32_16x16x32_bf16 v[10:13], v[10:13], v[18:21], v[156:159]
	s_nop 2
	ds_read2st64_b64 v[156:159], v186 offset0:40 offset1:44
	ds_read2st64_b64 v[172:175], v187 offset0:40 offset1:44
	v_mfma_f32_16x16x32_bf16 v[18:21], v[148:151], v[18:21], v[144:147]
	v_mfma_f32_16x16x32_bf16 v[10:13], v[168:171], v[14:17], v[10:13]
	s_waitcnt lgkmcnt(1)
	v_mov_b32_e32 v168, v156
	v_mov_b32_e32 v169, v157
	s_waitcnt lgkmcnt(0)
	v_mov_b32_e32 v170, v172
	v_mov_b32_e32 v171, v173
	v_mov_b32_e32 v172, v158
	v_mov_b32_e32 v173, v159
	v_mfma_f32_16x16x32_bf16 v[14:17], v[164:167], v[14:17], v[18:21]
	v_mfma_f32_16x16x32_bf16 v[2:5], v[176:179], v[136:139], v[2:5]
	ds_read2st64_b64 v[176:179], v186 offset0:56 offset1:60
	ds_read2st64_b64 v[180:183], v187 offset0:56 offset1:60
	s_cmp_eq_u32 s45, 0
	s_cbranch_scc1 .Ldscan_w0
	s_waitcnt vmcnt(32)
	s_branch .Ldscan_w1
.Ldscan_w0:
	s_waitcnt vmcnt(0)
.Ldscan_w1:
	s_cmp_eq_u32 s43, s38
	s_waitcnt lgkmcnt(0)
	v_mfma_f32_16x16x32_bf16 v[10:13], v[168:171], v[136:139], v[10:13]
	v_mov_b32_e32 v184, v176
	v_mov_b32_e32 v185, v177
	v_mov_b32_e32 v186, v180
	v_mfma_f32_16x16x32_bf16 v[14:17], v[172:175], v[136:139], v[14:17]
	v_mov_b32_e32 v187, v181
	v_mov_b32_e32 v180, v178
	v_mov_b32_e32 v181, v179
	v_mfma_f32_16x16x32_bf16 v[10:13], v[168:171], v[160:163], v[10:13]
	s_barrier
	v_mfma_f32_16x16x32_bf16 v[14:17], v[172:175], v[160:163], v[14:17]
	v_mfma_f32_16x16x32_bf16 v[10:13], v[184:187], v[136:139], v[10:13]
	v_mfma_f32_16x16x32_bf16 v[14:17], v[180:183], v[136:139], v[14:17]
	s_cbranch_scc1 .LBB0_229
	v_mov_b32_e32 v94, v143
	s_mov_b32 s45, s43
	v_mov_b32_e32 v159, v60
	v_mov_b32_e32 v158, v61
	v_mov_b32_e32 v157, v58
	v_mov_b32_e32 v156, v59
	v_mov_b32_e32 v155, v62
	v_mov_b32_e32 v154, v63
	v_mov_b32_e32 v153, v64
	v_mov_b32_e32 v152, v65
	v_mov_b32_e32 v151, v66
	v_mov_b32_e32 v150, v67
	v_mov_b32_e32 v149, v68
	v_mov_b32_e32 v148, v69
	v_mov_b32_e32 v147, v70
	v_mov_b32_e32 v146, v71
	v_mov_b32_e32 v145, v72
	v_mov_b32_e32 v144, v73
	v_mov_b32_e32 v138, v113
	v_mov_b32_e32 v139, v114
	v_mov_b32_e32 v140, v115
	v_mov_b32_e32 v141, v116
	v_mov_b32_e32 v18, v117
	v_mov_b32_e32 v19, v118
	v_mov_b32_e32 v20, v119
	v_mov_b32_e32 v21, v121
	v_mov_b32_e32 v132, v122
	v_mov_b32_e32 v134, v124
	v_mov_b32_e32 v136, v127
	v_mov_b32_e32 v137, v128
	v_mov_b32_e32 v120, v129
	v_mov_b32_e32 v123, v133
	v_mov_b32_e32 v125, v135
	v_mov_b32_e32 v126, v142
	v_mov_b32_e32 v60, v2
	v_mov_b32_e32 v61, v3
	v_mov_b32_e32 v58, v4
	v_mov_b32_e32 v59, v5
	v_mov_b32_e32 v62, v6
	v_mov_b32_e32 v63, v7
	v_mov_b32_e32 v64, v8
	v_mov_b32_e32 v65, v9
	v_mov_b32_e32 v66, v10
	v_mov_b32_e32 v67, v11
	v_mov_b32_e32 v68, v12
	v_mov_b32_e32 v69, v13
	v_mov_b32_e32 v70, v14
	v_mov_b32_e32 v71, v15
	v_mov_b32_e32 v72, v16
	v_mov_b32_e32 v73, v17
	s_branch .LBB0_223

.LBB0_417:
	s_or_b64 exec, exec, s[0:1]
	v_lshlrev_b64 v[4:5], 7, v[128:129]
	s_waitcnt vmcnt(0)
	v_cvt_pk_bf16_f32 v6, v2, v3
	v_lshl_add_u64 v[2:3], v[4:5], 1, v[54:55]
	v_cmp_lt_u32_e32 vcc, 1, v9
	v_cmp_lt_u32_e64 s[0:1], v9, v8
	v_mov_b32_e32 v130, v131
	global_store_dword v[2:3], v6, off
	v_add_u32_e32 v10, -2, v128
	s_and_b64 s[48:49], vcc, s[0:1]
	v_lshlrev_b32_e32 v2, 2, v52
	v_mov_b64_e32 v[6:7], v[130:131]
	v_mov_b64_e32 v[4:5], v[130:131]
	v_add_u32_e32 v3, 1, v9
	v_cmp_ne_u32_e32 vcc, 0, v9
	v_cmp_lt_u32_e64 s[0:1], v3, v8
	s_and_b64 s[0:1], vcc, s[0:1]
	v_add_u32_e32 v11, -1, v128
	v_add_u32_e32 v3, 2, v9
	v_cmp_lt_u32_e64 s[36:37], v3, v8
	v_add_u32_e32 v3, 3, v9
	v_cmp_lt_u32_e64 s[38:39], v3, v8
	v_add_u32_e32 v12, 1, v128
	v_add_u32_e32 v3, 4, v9
	v_cmp_lt_u32_e64 s[40:41], v3, v8
	v_add_u32_e32 v13, 2, v128
	v_add_u32_e32 v248, 0x1880, v2
	v_mov_b32_e32 v249, 0
	v_lshl_add_u64 v[248:249], s[8:9], 0, v[248:249]
	s_cmp_eq_u64 s[48:49], 0
	s_cbranch_scc1 .Lprep_cz0
	v_mad_i64_i32 v[246:247], s[52:53], v10, s15, v[248:249]
	global_load_dwordx4 v[156:159], v[246:247], off
	global_load_dwordx4 v[176:179], v[246:247], off offset:1024
	global_load_dwordx4 v[206:209], v[246:247], off offset:2048
	s_branch .Lprep_cd0
.Lprep_cz0:
	v_mov_b32_e32 v156, 0
	v_mov_b32_e32 v157, 0
	v_mov_b32_e32 v158, 0
	v_mov_b32_e32 v159, 0
	v_mov_b32_e32 v176, 0
	v_mov_b32_e32 v177, 0
	v_mov_b32_e32 v178, 0
	v_mov_b32_e32 v179, 0
	v_mov_b32_e32 v206, 0
	v_mov_b32_e32 v207, 0
	v_mov_b32_e32 v208, 0
	v_mov_b32_e32 v209, 0
.Lprep_cd0:
	s_cmp_eq_u64 s[0:1], 0
	s_cbranch_scc1 .Lprep_cz1
	v_mad_i64_i32 v[246:247], s[52:53], v11, s15, v[248:249]
	global_load_dwordx4 v[160:163], v[246:247], off
	global_load_dwordx4 v[180:183], v[246:247], off offset:1024
	global_load_dwordx4 v[210:213], v[246:247], off offset:2048
	s_branch .Lprep_cd1
.Lprep_cz1:
	v_mov_b32_e32 v160, 0
	v_mov_b32_e32 v161, 0
	v_mov_b32_e32 v162, 0
	v_mov_b32_e32 v163, 0
	v_mov_b32_e32 v180, 0
	v_mov_b32_e32 v181, 0
	v_mov_b32_e32 v182, 0
	v_mov_b32_e32 v183, 0
	v_mov_b32_e32 v210, 0
	v_mov_b32_e32 v211, 0
	v_mov_b32_e32 v212, 0
	v_mov_b32_e32 v213, 0
.Lprep_cd1:
	s_cmp_eq_u64 s[36:37], 0
	s_cbranch_scc1 .Lprep_cz2
	v_mad_i64_i32 v[246:247], s[52:53], v128, s15, v[248:249]
	global_load_dwordx4 v[164:167], v[246:247], off
	global_load_dwordx4 v[184:187], v[246:247], off offset:1024
	global_load_dwordx4 v[214:217], v[246:247], off offset:2048
	s_branch .Lprep_cd2
.Lprep_cz2:
	v_mov_b32_e32 v164, 0
	v_mov_b32_e32 v165, 0
	v_mov_b32_e32 v166, 0
	v_mov_b32_e32 v167, 0
	v_mov_b32_e32 v184, 0
	v_mov_b32_e32 v185, 0
	v_mov_b32_e32 v186, 0
	v_mov_b32_e32 v187, 0
	v_mov_b32_e32 v214, 0
	v_mov_b32_e32 v215, 0
	v_mov_b32_e32 v216, 0
	v_mov_b32_e32 v217, 0
.Lprep_cd2:
	s_cmp_eq_u64 s[38:39], 0
	s_cbranch_scc1 .Lprep_cz3
	v_mad_i64_i32 v[246:247], s[52:53], v12, s15, v[248:249]
	global_load_dwordx4 v[168:171], v[246:247], off
	global_load_dwordx4 v[188:191], v[246:247], off offset:1024
	global_load_dwordx4 v[218:221], v[246:247], off offset:2048
	s_branch .Lprep_cd3
.Lprep_cz3:
	v_mov_b32_e32 v168, 0
	v_mov_b32_e32 v169, 0
	v_mov_b32_e32 v170, 0
	v_mov_b32_e32 v171, 0
	v_mov_b32_e32 v188, 0
	v_mov_b32_e32 v189, 0
	v_mov_b32_e32 v190, 0
	v_mov_b32_e32 v191, 0
	v_mov_b32_e32 v218, 0
	v_mov_b32_e32 v219, 0
	v_mov_b32_e32 v220, 0
	v_mov_b32_e32 v221, 0
.Lprep_cd3:
	s_cmp_eq_u64 s[40:41], 0
	s_cbranch_scc1 .Lprep_cz4
	v_mad_i64_i32 v[246:247], s[52:53], v13, s15, v[248:249]
	global_load_dwordx4 v[172:175], v[246:247], off
	global_load_dwordx4 v[192:195], v[246:247], off offset:1024
	global_load_dwordx4 v[222:225], v[246:247], off offset:2048
	s_branch .Lprep_cd4
.Lprep_cz4:
	v_mov_b32_e32 v172, 0
	v_mov_b32_e32 v173, 0
	v_mov_b32_e32 v174, 0
	v_mov_b32_e32 v175, 0
	v_mov_b32_e32 v192, 0
	v_mov_b32_e32 v193, 0
	v_mov_b32_e32 v194, 0
	v_mov_b32_e32 v195, 0
	v_mov_b32_e32 v222, 0
	v_mov_b32_e32 v223, 0
	v_mov_b32_e32 v224, 0
	v_mov_b32_e32 v225, 0
.Lprep_cd4:
	global_load_dwordx4 v[226:229], v[60:61], off
	global_load_dwordx4 v[230:233], v[62:63], off offset:-3072
	global_load_dwordx4 v[234:237], v[62:63], off
	global_load_dwordx4 v[238:241], v[64:65], off
	global_load_dwordx4 v[242:245], v[66:67], off
	s_waitcnt vmcnt(0)
	v_pk_fma_f32 v[6:7], v[156:157], v[226:227], 0 op_sel_hi:[1,1,0]
	v_pk_fma_f32 v[4:5], v[158:159], v[228:229], 0 op_sel_hi:[1,1,0]
	v_pk_fma_f32 v[6:7], v[160:161], v[230:231], v[6:7]
	v_pk_fma_f32 v[4:5], v[162:163], v[232:233], v[4:5]
	v_pk_fma_f32 v[6:7], v[164:165], v[234:235], v[6:7]
	v_pk_fma_f32 v[4:5], v[166:167], v[236:237], v[4:5]
	v_pk_fma_f32 v[6:7], v[168:169], v[238:239], v[6:7]
	v_pk_fma_f32 v[4:5], v[170:171], v[240:241], v[4:5]
	v_pk_fma_f32 v[6:7], v[172:173], v[242:243], v[6:7]
	v_pk_fma_f32 v[4:5], v[174:175], v[244:245], v[4:5]
	global_load_dwordx4 v[226:229], v[60:61], off offset:1024
	global_load_dwordx4 v[230:233], v[62:63], off offset:-2048
	global_load_dwordx4 v[234:237], v[62:63], off offset:1024
	global_load_dwordx4 v[238:241], v[64:65], off offset:1024
	global_load_dwordx4 v[242:245], v[66:67], off offset:1024
	v_mul_f32_e32 v2, 0xbfb8aa3b, v5
	v_exp_f32_e32 v9, v2
	v_mul_f32_e32 v2, 0xbfb8aa3b, v4
	v_exp_f32_e32 v8, v2
	v_mul_f32_e32 v2, 0xbfb8aa3b, v7
	v_exp_f32_e32 v17, v2
	v_mul_f32_e32 v2, 0xbfb8aa3b, v6
	v_exp_f32_e32 v16, v2
	v_pk_add_f32 v[8:9], v[8:9], 1.0 op_sel_hi:[1,0]
	v_mad_i64_i32 v[2:3], s[50:51], v128, s12, v[112:113]
	v_pk_add_f32 v[16:17], v[16:17], 1.0 op_sel_hi:[1,0]
	v_mov_b32_e32 v130, v131
	v_div_scale_f32 v18, s[50:51], v17, v17, v7
	v_rcp_f32_e32 v19, v18
	s_nop 0
	v_fma_f32 v20, -v18, v19, 1.0
	v_fmac_f32_e32 v19, v20, v19
	v_div_scale_f32 v20, vcc, v7, v17, v7
	v_mul_f32_e32 v21, v20, v19
	v_fma_f32 v22, -v18, v21, v20
	v_fmac_f32_e32 v21, v22, v19
	v_fma_f32 v18, -v18, v21, v20
	v_div_fmas_f32 v18, v18, v19, v21
	v_div_fixup_f32 v17, v18, v17, v7
	v_div_scale_f32 v7, s[50:51], v16, v16, v6
	v_rcp_f32_e32 v18, v7
	s_nop 0
	v_fma_f32 v19, -v7, v18, 1.0
	v_fmac_f32_e32 v18, v19, v18
	v_div_scale_f32 v19, vcc, v6, v16, v6
	v_mul_f32_e32 v20, v19, v18
	v_fma_f32 v21, -v7, v20, v19
	v_fmac_f32_e32 v20, v21, v18
	v_fma_f32 v7, -v7, v20, v19
	v_div_fmas_f32 v7, v7, v18, v20
	v_div_scale_f32 v18, s[50:51], v9, v9, v5
	v_rcp_f32_e32 v19, v18
	v_div_fixup_f32 v16, v7, v16, v6
	v_pk_mul_f32 v[6:7], v[16:17], v[16:17]
	v_fma_f32 v20, -v18, v19, 1.0
	v_fmac_f32_e32 v19, v20, v19
	v_div_scale_f32 v20, vcc, v5, v9, v5
	v_mul_f32_e32 v21, v20, v19
	v_fma_f32 v22, -v18, v21, v20
	v_fmac_f32_e32 v21, v22, v19
	v_fma_f32 v18, -v18, v21, v20
	v_div_fmas_f32 v18, v18, v19, v21
	v_div_fixup_f32 v5, v18, v9, v5
	v_div_scale_f32 v9, s[50:51], v8, v8, v4
	v_rcp_f32_e32 v18, v9
	v_add_f32_e32 v6, v6, v7
	v_fma_f32 v19, -v9, v18, 1.0
	v_fmac_f32_e32 v18, v19, v18
	v_div_scale_f32 v19, vcc, v4, v8, v4
	v_mul_f32_e32 v20, v19, v18
	v_fma_f32 v21, -v9, v20, v19
	v_fmac_f32_e32 v20, v21, v18
	v_fma_f32 v9, -v9, v20, v19
	v_div_fmas_f32 v9, v9, v18, v20
	v_div_fixup_f32 v4, v9, v8, v4
	v_pk_mul_f32 v[8:9], v[4:5], v[4:5]
	s_nop 0
	v_add_f32_e32 v6, v6, v8
	v_add_f32_e32 v6, v6, v9
	ds_bpermute_b32 v7, v69, v6
	s_waitcnt lgkmcnt(0)
	v_add_f32_e32 v6, v6, v7
	ds_bpermute_b32 v7, v79, v6
	s_waitcnt lgkmcnt(0)
	v_add_f32_e32 v6, v6, v7
	ds_bpermute_b32 v7, v138, v6
	s_waitcnt lgkmcnt(0)
	v_add_f32_e32 v6, v6, v7
	ds_bpermute_b32 v7, v139, v6
	s_waitcnt lgkmcnt(0)
	v_add_f32_e32 v6, v6, v7
	v_add_f32_e32 v6, 0x358637bd, v6
	v_cmp_gt_f32_e32 vcc, s14, v6
	v_mul_f32_e32 v7, 0x4b800000, v6
	s_nop 0
	v_cndmask_b32_e32 v6, v6, v7, vcc
	v_rsq_f32_e32 v6, v6
	s_nop 0
	v_mul_f32_e32 v7, 0x45800000, v6
	v_cndmask_b32_e32 v6, v6, v7, vcc
	v_mul_f32_e32 v8, 0x3e000000, v6
	v_pk_mul_f32 v[6:7], v[4:5], v[8:9] op_sel_hi:[1,0]
	v_pk_mul_f32 v[4:5], v[16:17], v[8:9] op_sel_hi:[1,0]
	global_store_dwordx4 v[2:3], v[4:7], off
	v_lshlrev_b32_e32 v8, 2, v68
	s_nop 0
	v_mov_b64_e32 v[6:7], v[130:131]
	v_mov_b64_e32 v[4:5], v[130:131]
	s_waitcnt vmcnt(1)
	v_pk_fma_f32 v[6:7], v[176:177], v[226:227], 0 op_sel_hi:[1,1,0]
	v_pk_fma_f32 v[4:5], v[178:179], v[228:229], 0 op_sel_hi:[1,1,0]
	v_pk_fma_f32 v[6:7], v[180:181], v[230:231], v[6:7]
	v_pk_fma_f32 v[4:5], v[182:183], v[232:233], v[4:5]
	v_pk_fma_f32 v[6:7], v[184:185], v[234:235], v[6:7]
	v_pk_fma_f32 v[4:5], v[186:187], v[236:237], v[4:5]
	v_pk_fma_f32 v[6:7], v[188:189], v[238:239], v[6:7]
	v_pk_fma_f32 v[4:5], v[190:191], v[240:241], v[4:5]
	v_pk_fma_f32 v[6:7], v[192:193], v[242:243], v[6:7]
	v_pk_fma_f32 v[4:5], v[194:195], v[244:245], v[4:5]
	global_load_dwordx4 v[226:229], v[60:61], off offset:2048
	global_load_dwordx4 v[230:233], v[62:63], off offset:-1024
	global_load_dwordx4 v[234:237], v[62:63], off offset:2048
	global_load_dwordx4 v[238:241], v[64:65], off offset:2048
	global_load_dwordx4 v[242:245], v[66:67], off offset:2048
	v_mul_f32_e32 v16, 0xbfb8aa3b, v7
	v_exp_f32_e32 v17, v16
	v_mul_f32_e32 v16, 0xbfb8aa3b, v6
	v_exp_f32_e32 v16, v16
	v_mul_f32_e32 v8, 0xbfb8aa3b, v5
	v_exp_f32_e32 v9, v8
	v_mul_f32_e32 v8, 0xbfb8aa3b, v4
	v_pk_add_f32 v[16:17], v[16:17], 1.0 op_sel_hi:[1,0]
	v_exp_f32_e32 v8, v8
	v_div_scale_f32 v18, s[50:51], v17, v17, v7
	v_rcp_f32_e32 v19, v18
	v_pk_add_f32 v[8:9], v[8:9], 1.0 op_sel_hi:[1,0]
	v_mov_b32_e32 v130, v131
	v_fma_f32 v20, -v18, v19, 1.0
	v_fmac_f32_e32 v19, v20, v19
	v_div_scale_f32 v20, vcc, v7, v17, v7
	v_mul_f32_e32 v21, v20, v19
	v_fma_f32 v22, -v18, v21, v20
	v_fmac_f32_e32 v21, v22, v19
	v_fma_f32 v18, -v18, v21, v20
	v_div_fmas_f32 v18, v18, v19, v21
	v_div_fixup_f32 v17, v18, v17, v7
	v_div_scale_f32 v7, s[50:51], v16, v16, v6
	v_rcp_f32_e32 v18, v7
	s_nop 0
	v_fma_f32 v19, -v7, v18, 1.0
	v_fmac_f32_e32 v18, v19, v18
	v_div_scale_f32 v19, vcc, v6, v16, v6
	v_mul_f32_e32 v20, v19, v18
	v_fma_f32 v21, -v7, v20, v19
	v_fmac_f32_e32 v20, v21, v18
	v_fma_f32 v7, -v7, v20, v19
	v_div_fmas_f32 v7, v7, v18, v20
	v_div_scale_f32 v18, s[50:51], v9, v9, v5
	v_rcp_f32_e32 v19, v18
	v_div_fixup_f32 v16, v7, v16, v6
	v_pk_mul_f32 v[6:7], v[16:17], v[16:17]
	v_fma_f32 v20, -v18, v19, 1.0
	v_fmac_f32_e32 v19, v20, v19
	v_div_scale_f32 v20, vcc, v5, v9, v5
	v_mul_f32_e32 v21, v20, v19
	v_fma_f32 v22, -v18, v21, v20
	v_fmac_f32_e32 v21, v22, v19
	v_fma_f32 v18, -v18, v21, v20
	v_div_fmas_f32 v18, v18, v19, v21
	v_div_fixup_f32 v5, v18, v9, v5
	v_div_scale_f32 v9, s[50:51], v8, v8, v4
	v_rcp_f32_e32 v18, v9
	v_add_f32_e32 v6, v6, v7
	v_fma_f32 v19, -v9, v18, 1.0
	v_fmac_f32_e32 v18, v19, v18
	v_div_scale_f32 v19, vcc, v4, v8, v4
	v_mul_f32_e32 v20, v19, v18
	v_fma_f32 v21, -v9, v20, v19
	v_fmac_f32_e32 v20, v21, v18
	v_fma_f32 v9, -v9, v20, v19
	v_div_fmas_f32 v9, v9, v18, v20
	v_div_fixup_f32 v4, v9, v8, v4
	v_pk_mul_f32 v[8:9], v[4:5], v[4:5]
	s_nop 0
	v_add_f32_e32 v6, v6, v8
	v_add_f32_e32 v6, v6, v9
	ds_bpermute_b32 v7, v69, v6
	s_waitcnt lgkmcnt(0)
	v_add_f32_e32 v6, v6, v7
	ds_bpermute_b32 v7, v79, v6
	s_waitcnt lgkmcnt(0)
	v_add_f32_e32 v6, v6, v7
	ds_bpermute_b32 v7, v138, v6
	s_waitcnt lgkmcnt(0)
	v_add_f32_e32 v6, v6, v7
	ds_bpermute_b32 v7, v139, v6
	s_waitcnt lgkmcnt(0)
	v_add_f32_e32 v6, v6, v7
	v_add_f32_e32 v6, 0x358637bd, v6
	v_cmp_gt_f32_e32 vcc, s14, v6
	v_mul_f32_e32 v7, 0x4b800000, v6
	s_nop 0
	v_cndmask_b32_e32 v6, v6, v7, vcc
	v_rsq_f32_e32 v6, v6
	s_nop 0
	v_mul_f32_e32 v7, 0x45800000, v6
	v_cndmask_b32_e32 v8, v6, v7, vcc
	v_pk_mul_f32 v[6:7], v[4:5], v[8:9] op_sel_hi:[1,0]
	v_pk_mul_f32 v[4:5], v[16:17], v[8:9] op_sel_hi:[1,0]
	global_store_dwordx4 v[2:3], v[4:7], off offset:1024
	v_lshlrev_b32_e32 v8, 2, v78
	s_nop 0
	v_mov_b64_e32 v[6:7], v[130:131]
	v_mov_b64_e32 v[4:5], v[130:131]
	s_waitcnt vmcnt(1)
	v_pk_fma_f32 v[6:7], v[206:207], v[226:227], 0 op_sel_hi:[1,1,0]
	v_pk_fma_f32 v[4:5], v[208:209], v[228:229], 0 op_sel_hi:[1,1,0]
	v_pk_fma_f32 v[6:7], v[210:211], v[230:231], v[6:7]
	v_pk_fma_f32 v[4:5], v[212:213], v[232:233], v[4:5]
	v_pk_fma_f32 v[6:7], v[214:215], v[234:235], v[6:7]
	v_pk_fma_f32 v[4:5], v[216:217], v[236:237], v[4:5]
	v_pk_fma_f32 v[6:7], v[218:219], v[238:239], v[6:7]
	v_pk_fma_f32 v[4:5], v[220:221], v[240:241], v[4:5]
	v_pk_fma_f32 v[6:7], v[222:223], v[242:243], v[6:7]
	v_pk_fma_f32 v[4:5], v[224:225], v[244:245], v[4:5]
	v_mul_f32_e32 v10, 0xbfb8aa3b, v7
	v_exp_f32_e32 v11, v10
	v_mul_f32_e32 v10, 0xbfb8aa3b, v6
	v_exp_f32_e32 v10, v10
	v_mul_f32_e32 v8, 0xbfb8aa3b, v5
	v_exp_f32_e32 v9, v8
	v_mul_f32_e32 v8, 0xbfb8aa3b, v4
	v_pk_add_f32 v[10:11], v[10:11], 1.0 op_sel_hi:[1,0]
	v_exp_f32_e32 v8, v8
	v_div_scale_f32 v12, s[0:1], v11, v11, v7
	v_rcp_f32_e32 v13, v12
	v_pk_add_f32 v[8:9], v[8:9], 1.0 op_sel_hi:[1,0]
	v_mov_b32_e32 v127, v131
	s_mov_b32 s20, 0x800000
	v_fma_f32 v16, -v12, v13, 1.0
	v_fmac_f32_e32 v13, v16, v13
	v_div_scale_f32 v16, vcc, v7, v11, v7
	v_mul_f32_e32 v17, v16, v13
	v_fma_f32 v18, -v12, v17, v16
	v_fmac_f32_e32 v17, v18, v13
	v_fma_f32 v12, -v12, v17, v16
	v_div_fmas_f32 v12, v12, v13, v17
	v_div_fixup_f32 v7, v12, v11, v7
	v_div_scale_f32 v11, s[0:1], v10, v10, v6
	v_rcp_f32_e32 v12, v11
	s_mov_b32 s27, 0x3f317217
	s_mov_b32 s40, 0x7f800000
	s_mov_b32 s41, 0xc1a00000
	v_fma_f32 v13, -v11, v12, 1.0
	v_fmac_f32_e32 v12, v13, v12
	v_div_scale_f32 v13, vcc, v6, v10, v6
	v_mul_f32_e32 v16, v13, v12
	v_fma_f32 v17, -v11, v16, v13
	v_fmac_f32_e32 v16, v17, v12
	v_fma_f32 v11, -v11, v16, v13
	v_div_fmas_f32 v11, v11, v12, v16
	v_div_fixup_f32 v6, v11, v10, v6
	v_div_scale_f32 v10, s[0:1], v9, v9, v5
	v_rcp_f32_e32 v11, v10
	s_mov_b32 s50, 0xbd800000
	s_mov_b32 s14, 0x800000
	s_mov_b32 s48, 0x3f317217
	v_fma_f32 v12, -v10, v11, 1.0
	v_fmac_f32_e32 v11, v12, v11
	v_div_scale_f32 v12, vcc, v5, v9, v5
	v_mul_f32_e32 v13, v12, v11
	v_fma_f32 v16, -v10, v13, v12
	v_fmac_f32_e32 v13, v16, v11
	v_fma_f32 v10, -v10, v13, v12
	v_div_fmas_f32 v10, v10, v11, v13
	v_div_fixup_f32 v9, v10, v9, v5
	v_div_scale_f32 v5, s[0:1], v8, v8, v4
	v_rcp_f32_e32 v10, v5
	s_nop 0
	v_fma_f32 v11, -v5, v10, 1.0
	v_fmac_f32_e32 v10, v11, v10
	v_div_scale_f32 v11, vcc, v4, v8, v4
	v_mul_f32_e32 v12, v11, v10
	v_fma_f32 v13, -v5, v12, v11
	v_fmac_f32_e32 v12, v13, v10
	v_fma_f32 v5, -v5, v12, v11
	v_div_fmas_f32 v5, v5, v10, v12
	v_div_fixup_f32 v8, v5, v8, v4
	global_store_dwordx4 v[2:3], v[6:9], off offset:2048
	v_lshl_add_u64 v[2:3], v[132:133], 0, v[126:127]
	v_lshl_add_u64 v[16:17], v[2:3], 0, s[54:55]
	v_add_co_u32_e32 v2, vcc, s33, v2
	s_nop 1
	v_addc_co_u32_e32 v3, vcc, 0, v3, vcc
	global_load_dwordx4 v[10:13], v[2:3], off offset:2048
	s_nop 0
	global_load_dwordx4 v[2:5], v[16:17], off offset:48
	global_load_dwordx4 v[6:9], v[16:17], off offset:32
	s_nop 0
	global_load_dwordx4 v[16:19], v[16:17], off offset:16
	s_nop 0
	global_load_dwordx4 v[20:23], v[56:57], off
	global_load_dwordx4 v[24:27], v[88:89], off
	global_load_dwordx4 v[28:31], v[88:89], off offset:512
	global_load_dwordx4 v[32:35], v[88:89], off offset:1024
	global_load_dwordx4 v[36:39], v[88:89], off offset:1536
	global_load_dwordx4 v[134:137], v[88:89], off offset:2048
	global_load_dwordx4 v[144:147], v[88:89], off offset:2560
	global_load_dwordx4 v[148:151], v[88:89], off offset:3072
	global_load_dwordx4 v[152:155], v[88:89], off offset:3584
	s_waitcnt vmcnt(7)
	v_pk_fma_f32 v[20:21], v[10:11], v[24:25], v[20:21] op_sel_hi:[0,1,1]
	v_pk_fma_f32 v[22:23], v[10:11], v[26:27], v[22:23] op_sel_hi:[0,1,1]
	s_waitcnt vmcnt(6)
	v_pk_fma_f32 v[20:21], v[10:11], v[28:29], v[20:21] op_sel:[1,0,0]
	v_pk_fma_f32 v[10:11], v[10:11], v[30:31], v[22:23] op_sel:[1,0,0]
	v_mov_b32_e32 v24, v13
	s_waitcnt vmcnt(5)
	v_pk_fma_f32 v[10:11], v[12:13], v[34:35], v[10:11] op_sel_hi:[0,1,1]
	s_waitcnt vmcnt(4)
	v_pk_fma_f32 v[10:11], v[24:25], v[38:39], v[10:11] op_sel_hi:[0,1,1]
	v_pk_fma_f32 v[20:21], v[12:13], v[32:33], v[20:21] op_sel_hi:[0,1,1]
	s_waitcnt vmcnt(3)
	v_pk_fma_f32 v[10:11], v[16:17], v[136:137], v[10:11] op_sel_hi:[0,1,1]
	v_pk_fma_f32 v[20:21], v[24:25], v[36:37], v[20:21] op_sel_hi:[0,1,1]
	s_waitcnt vmcnt(2)
	v_pk_fma_f32 v[10:11], v[16:17], v[146:147], v[10:11] op_sel:[1,0,0]
	v_pk_fma_f32 v[20:21], v[16:17], v[134:135], v[20:21] op_sel_hi:[0,1,1]
	v_mov_b32_e32 v28, v19
	s_waitcnt vmcnt(1)
	v_pk_fma_f32 v[10:11], v[18:19], v[150:151], v[10:11] op_sel_hi:[0,1,1]
	v_pk_fma_f32 v[20:21], v[16:17], v[144:145], v[20:21] op_sel:[1,0,0]
	v_lshl_add_u64 v[134:135], v[58:59], 0, v[14:15]
	global_load_dwordx4 v[14:17], v[92:93], off
	s_waitcnt vmcnt(1)
	v_pk_fma_f32 v[136:137], v[28:29], v[154:155], v[10:11] op_sel_hi:[0,1,1]
	global_load_dwordx4 v[10:13], v[90:91], off
	global_load_dwordx4 v[22:25], v[96:97], off
	v_pk_fma_f32 v[20:21], v[18:19], v[148:149], v[20:21] op_sel_hi:[0,1,1]
	v_pk_fma_f32 v[20:21], v[28:29], v[152:153], v[20:21] op_sel_hi:[0,1,1]
	global_load_dwordx4 v[30:33], v[100:101], off
	global_load_dwordx4 v[34:37], v[102:103], off
	global_load_dwordx4 v[38:41], v[104:105], off
	global_load_dwordx4 v[26:29], v[98:99], off
	s_waitcnt vmcnt(5)
	v_pk_fma_f32 v[10:11], v[6:7], v[10:11], v[20:21] op_sel_hi:[0,1,1]
	global_load_dwordx4 v[18:21], v[94:95], off
	v_pk_fma_f32 v[10:11], v[6:7], v[14:15], v[10:11] op_sel:[1,0,0]
	v_pk_fma_f32 v[12:13], v[6:7], v[12:13], v[136:137] op_sel_hi:[0,1,1]
	v_pk_fma_f32 v[6:7], v[6:7], v[16:17], v[12:13] op_sel:[1,0,0]
	s_waitcnt vmcnt(0)
	v_pk_fma_f32 v[14:15], v[8:9], v[18:19], v[10:11] op_sel_hi:[0,1,1]
	v_mov_b32_e32 v10, v9
	v_pk_fma_f32 v[14:15], v[10:11], v[22:23], v[14:15] op_sel_hi:[0,1,1]
	v_pk_fma_f32 v[14:15], v[2:3], v[26:27], v[14:15] op_sel_hi:[0,1,1]
	v_pk_fma_f32 v[14:15], v[2:3], v[30:31], v[14:15] op_sel:[1,0,0]
	v_mov_b32_e32 v18, v5
	v_pk_fma_f32 v[14:15], v[4:5], v[34:35], v[14:15] op_sel_hi:[0,1,1]
	v_pk_fma_f32 v[14:15], v[18:19], v[38:39], v[14:15] op_sel_hi:[0,1,1]
	v_mul_f32_e32 v5, 0xbfb8aa3b, v14
	v_exp_f32_e32 v5, v5
	s_nop 0
	v_add_f32_e32 v5, 1.0, v5
	v_cmp_gt_f32_e32 vcc, s20, v5
	s_nop 1
	v_cndmask_b32_e64 v9, 0, 32, vcc
	v_ldexp_f32 v5, v5, v9
	v_log_f32_e32 v5, v5
	s_nop 0
	v_mul_f32_e32 v9, 0x3f317217, v5
	v_fma_f32 v9, v5, s27, -v9
	v_fmac_f32_e32 v9, 0x3377d1cf, v5
	v_fmac_f32_e32 v9, 0x3f317217, v5
	v_cmp_lt_f32_e64 s[0:1], |v5|, s40
	s_nop 1
	v_cndmask_b32_e64 v5, v5, v9, s[0:1]
	v_cndmask_b32_e32 v9, 0, v203, vcc
	v_sub_f32_e32 v5, v5, v9
	v_mul_f32_e32 v9, 0xbfb8aa3b, v15
	v_exp_f32_e32 v9, v9
	v_cmp_gt_f32_e32 vcc, s41, v14
	v_cmp_gt_f32_e64 s[0:1], s41, v15
	v_add_f32_e32 v9, 1.0, v9
	v_cmp_gt_f32_e64 s[36:37], s20, v9
	v_cndmask_b32_e64 v14, v5, -v14, vcc
	s_nop 0
	v_cndmask_b32_e64 v11, 0, 32, s[36:37]
	v_ldexp_f32 v9, v9, v11
	v_log_f32_e32 v9, v9
	s_nop 0
	v_mul_f32_e32 v11, 0x3f317217, v9
	v_fma_f32 v11, v9, s27, -v11
	v_fmac_f32_e32 v11, 0x3377d1cf, v9
	v_fmac_f32_e32 v11, 0x3f317217, v9
	v_cmp_lt_f32_e64 s[38:39], |v9|, s40
	s_nop 1
	v_cndmask_b32_e64 v9, v9, v11, s[38:39]
	v_cndmask_b32_e64 v11, 0, v203, s[36:37]
	v_sub_f32_e32 v9, v9, v11
	v_pk_fma_f32 v[6:7], v[8:9], v[20:21], v[6:7] op_sel_hi:[0,1,1]
	v_pk_fma_f32 v[6:7], v[10:11], v[24:25], v[6:7] op_sel_hi:[0,1,1]
	v_pk_fma_f32 v[6:7], v[2:3], v[28:29], v[6:7] op_sel_hi:[0,1,1]
	v_pk_fma_f32 v[2:3], v[2:3], v[32:33], v[6:7] op_sel:[1,0,0]
	v_cndmask_b32_e64 v15, v9, -v15, s[0:1]
	v_pk_fma_f32 v[2:3], v[4:5], v[36:37], v[2:3] op_sel_hi:[0,1,1]
	v_pk_fma_f32 v[2:3], v[18:19], v[40:41], v[2:3] op_sel_hi:[0,1,1]
	v_mul_f32_e32 v4, 0xbfb8aa3b, v2
	v_exp_f32_e32 v4, v4
	v_pk_mul_f32 v[14:15], v[14:15], s[50:51] op_sel_hi:[1,0]
	v_add_f32_e32 v4, 1.0, v4
	v_cmp_gt_f32_e32 vcc, s20, v4
	s_nop 1
	v_cndmask_b32_e64 v5, 0, 32, vcc
	v_ldexp_f32 v4, v4, v5
	v_log_f32_e32 v4, v4
	s_nop 0
	v_mul_f32_e32 v5, 0x3f317217, v4
	v_fma_f32 v5, v4, s27, -v5
	v_fmac_f32_e32 v5, 0x3377d1cf, v4
	v_fmac_f32_e32 v5, 0x3f317217, v4
	v_cmp_lt_f32_e64 s[0:1], |v4|, s40
	s_nop 1
	v_cndmask_b32_e64 v4, v4, v5, s[0:1]
	v_cndmask_b32_e32 v5, 0, v203, vcc
	v_sub_f32_e32 v4, v4, v5
	v_mul_f32_e32 v5, 0xbfb8aa3b, v3
	v_exp_f32_e32 v5, v5
	v_cmp_gt_f32_e32 vcc, s41, v2
	v_cmp_gt_f32_e64 s[0:1], s41, v3
	v_add_f32_e32 v5, 1.0, v5
	v_cmp_gt_f32_e64 s[36:37], s20, v5
	v_cndmask_b32_e64 v2, v4, -v2, vcc
	s_nop 0
	v_cndmask_b32_e64 v6, 0, 32, s[36:37]
	v_ldexp_f32 v5, v5, v6
	v_log_f32_e32 v5, v5
	s_nop 0
	v_mul_f32_e32 v6, 0x3f317217, v5
	v_fma_f32 v6, v5, s27, -v6
	v_fmac_f32_e32 v6, 0x3377d1cf, v5
	v_fmac_f32_e32 v6, 0x3f317217, v5
	v_cmp_lt_f32_e64 s[38:39], |v5|, s40
	s_mov_b32 s27, 0x7f800000
	s_nop 0
	v_cndmask_b32_e64 v5, v5, v6, s[38:39]
	v_cndmask_b32_e64 v6, 0, v203, s[36:37]
	v_sub_f32_e32 v5, v5, v6
	v_cndmask_b32_e64 v3, v5, -v3, s[0:1]
	v_pk_mul_f32 v[16:17], v[2:3], s[50:51] op_sel_hi:[1,0]
	s_mov_b64 s[0:1], 0
	global_store_dwordx4 v[134:135], v[14:17], off
	s_and_saveexec_b64 s[36:37], s[30:31]
	s_xor_b64 s[36:37], exec, s[36:37]
	s_cbranch_execz .LBB0_452
	s_and_saveexec_b64 s[38:39], s[6:7]
	s_xor_b64 s[38:39], exec, s[38:39]
	s_cbranch_execz .LBB0_442
	v_lshlrev_b32_e32 v130, 2, v46
	v_lshl_add_u64 v[2:3], v[132:133], 0, v[130:131]
	v_add_co_u32_e32 v2, vcc, 0x2000, v2
	s_mov_b64 s[0:1], exec
	s_nop 0
	v_addc_co_u32_e32 v3, vcc, 0, v3, vcc
	global_load_dword v4, v[108:109], off offset:-32
	s_nop 0
	global_load_dword v2, v[2:3], off offset:2176
	s_nop 0
	global_load_dword v3, v[106:107], off offset:-32
	s_waitcnt vmcnt(1)
	v_add_f32_e32 v2, v2, v4
	v_mul_f32_e32 v4, 0x3fb8aa3b, v2
	v_exp_f32_e32 v4, v4
	s_waitcnt vmcnt(0)
	v_mul_f32_e32 v3, 0x3fb8aa3b, v3
	v_exp_f32_e32 v3, v3
	v_add_f32_e32 v4, 1.0, v4
	v_cmp_gt_f32_e32 vcc, s14, v4
	s_nop 1
	v_cndmask_b32_e64 v5, 0, 32, vcc
	v_ldexp_f32 v4, v4, v5
	v_log_f32_e32 v4, v4
	v_cndmask_b32_e32 v5, 0, v203, vcc
	v_mul_f32_e32 v6, 0x3f317217, v4
	v_fma_f32 v6, v4, s48, -v6
	v_fmac_f32_e32 v6, 0x3377d1cf, v4
	v_fmac_f32_e32 v6, 0x3f317217, v4
	v_cmp_lt_f32_e64 vcc, |v4|, s27
	s_mov_b32 s27, 0x41a00000
	s_nop 0
	v_cndmask_b32_e32 v4, v4, v6, vcc
	v_sub_f32_e32 v4, v4, v5
	v_cmp_lt_f32_e32 vcc, s27, v2
	s_nop 1
	v_cndmask_b32_e32 v2, v4, v2, vcc
	v_mul_f32_e64 v6, v2, -v3
	v_lshl_add_u32 v2, v128, 3, v47

.LBB0_443:
	s_or_b64 exec, exec, s[36:37]
	s_and_saveexec_b64 s[36:37], s[0:1]
	s_cbranch_execz .LBB0_408
	s_branch .LBB0_454
.LBB0_452:
	s_or_saveexec_b64 s[36:37], s[36:37]
	v_mov_b64_e32 v[4:5], 0x9e40000
	s_xor_b64 exec, exec, s[36:37]
	s_cbranch_execz .LBB0_443
